# GEMM-in epilogue stores marked nt (streaming, keeps A/B panels in L2)
# speedup vs baseline: 1.0143x; 1.0028x over previous
.LBB0_517:
	v_cvt_pk_bf16_f32 v4, v4, v5
	v_cvt_pk_bf16_f32 v5, v6, v7
	v_cvt_pk_bf16_f32 v6, v0, v1
	v_cvt_pk_bf16_f32 v7, v2, v3
	s_and_b64 vcc, exec, s[6:7]
	s_mov_b32 s26, s18
	s_mov_b32 s28, s24
	s_mov_b64 s[4:5], s[38:39]
	s_mov_b64 s[0:1], s[34:35]
	global_store_dwordx4 v[10:11], v[4:7], off nt
	s_cbranch_vccnz .LBB0_554

.LBB0_521:
	s_add_u32 s4, s0, 0xfffc0080
	s_addc_u32 s5, s1, -1
	s_add_i32 s62, 0, 0x10000
	v_add_u32_e32 v8, s62, v146
	ds_read_b128 v[162:165], v8
	ds_read_b128 v[166:169], v8 offset:1024
	ds_read_b128 v[170:173], v8 offset:2048
	ds_read_b128 v[174:177], v8 offset:3072
	s_cmp_eq_u32 s43, 12
	s_cselect_b32 s37, s25, s5
	s_cselect_b32 s36, s29, s4
	s_cselect_b32 s5, s19, s42
	s_cselect_b32 s4, s40, s41
	v_lshl_add_u64 v[144:145], s[0:1], 0, v[140:141]
	s_add_i32 m0, s44, 0xc000
	ds_read_b128 v[178:181], v160
	ds_read_b128 v[182:185], v160 offset:1024
	ds_read_b128 v[186:189], v160 offset:2048
	ds_read_b128 v[190:193], v160 offset:3072
	ds_read_b128 v[204:207], v160 offset:4096
	ds_read_b128 v[208:211], v160 offset:5120
	ds_read_b128 v[212:215], v160 offset:6144
	ds_read_b128 v[228:231], v160 offset:7168
	global_load_lds_dwordx4 v[144:145], off
	v_lshl_add_u64 v[144:145], s[0:1], 0, v[142:143]
	s_add_i32 m0, s44, 0xe000
	s_nop 0
	global_load_lds_dwordx4 v[144:145], off
	s_waitcnt lgkmcnt(8)
	s_barrier
	s_waitcnt lgkmcnt(0)
	s_setprio 1
	s_waitcnt lgkmcnt(0)
	v_mfma_f32_16x16x32_bf16 v[126:129], v[162:165], v[178:181], v[126:129]
	v_mfma_f32_16x16x32_bf16 v[122:125], v[170:173], v[178:181], v[122:125]
	v_mfma_f32_16x16x32_bf16 v[118:121], v[162:165], v[186:189], v[118:121]
	v_mfma_f32_16x16x32_bf16 v[110:113], v[170:173], v[186:189], v[110:113]
	v_mfma_f32_16x16x32_bf16 v[102:105], v[162:165], v[204:207], v[102:105]
	v_mfma_f32_16x16x32_bf16 v[94:97], v[170:173], v[204:207], v[94:97]
	v_mfma_f32_16x16x32_bf16 v[86:89], v[162:165], v[212:215], v[86:89]
	v_mfma_f32_16x16x32_bf16 v[78:81], v[170:173], v[212:215], v[78:81]
	v_mfma_f32_16x16x32_bf16 v[126:129], v[166:169], v[182:185], v[126:129]
	v_mfma_f32_16x16x32_bf16 v[122:125], v[174:177], v[182:185], v[122:125]
	v_mfma_f32_16x16x32_bf16 v[118:121], v[166:169], v[190:193], v[118:121]
	v_mfma_f32_16x16x32_bf16 v[110:113], v[174:177], v[190:193], v[110:113]
	v_mfma_f32_16x16x32_bf16 v[102:105], v[166:169], v[208:211], v[102:105]
	v_mfma_f32_16x16x32_bf16 v[94:97], v[174:177], v[208:211], v[94:97]
	v_mfma_f32_16x16x32_bf16 v[86:89], v[166:169], v[228:231], v[86:89]
	v_mfma_f32_16x16x32_bf16 v[78:81], v[174:177], v[228:231], v[78:81]
	s_setprio 0
	s_barrier
	s_add_i32 s64, 0, 0x14000
	s_add_i32 s62, s62, s3
	v_add_u32_e32 v8, s64, v146
	v_lshl_add_u64 v[144:145], s[4:5], 0, v[134:135]
	s_mov_b32 m0, s62
	ds_read_b128 v[232:235], v8
	ds_read_b128 v[236:239], v8 offset:1024
	ds_read_b128 v[240:243], v8 offset:2048
	ds_read_b128 v[244:247], v8 offset:3072
	global_load_lds_dwordx4 v[144:145], off
	v_lshl_add_u64 v[216:217], s[4:5], 0, v[130:131]
	s_add_i32 m0, s62, 0x2000
	s_nop 0
	global_load_lds_dwordx4 v[216:217], off
	s_barrier
	s_waitcnt lgkmcnt(0)
	s_setprio 1
	s_waitcnt lgkmcnt(0)
	v_mfma_f32_16x16x32_bf16 v[114:117], v[232:235], v[178:181], v[114:117]
	v_mfma_f32_16x16x32_bf16 v[106:109], v[240:243], v[178:181], v[106:109]
	v_mfma_f32_16x16x32_bf16 v[98:101], v[232:235], v[186:189], v[98:101]
	v_mfma_f32_16x16x32_bf16 v[90:93], v[240:243], v[186:189], v[90:93]
	v_mfma_f32_16x16x32_bf16 v[82:85], v[232:235], v[204:207], v[82:85]
	v_mfma_f32_16x16x32_bf16 v[74:77], v[240:243], v[204:207], v[74:77]
	v_mfma_f32_16x16x32_bf16 v[70:73], v[232:235], v[212:215], v[70:73]
	v_mfma_f32_16x16x32_bf16 v[66:69], v[240:243], v[212:215], v[66:69]
	v_mfma_f32_16x16x32_bf16 v[114:117], v[236:239], v[182:185], v[114:117]
	v_mfma_f32_16x16x32_bf16 v[106:109], v[244:247], v[182:185], v[106:109]
	v_mfma_f32_16x16x32_bf16 v[98:101], v[236:239], v[190:193], v[98:101]
	v_mfma_f32_16x16x32_bf16 v[90:93], v[244:247], v[190:193], v[90:93]
	v_mfma_f32_16x16x32_bf16 v[82:85], v[236:239], v[208:211], v[82:85]
	v_mfma_f32_16x16x32_bf16 v[74:77], v[244:247], v[208:211], v[74:77]
	v_mfma_f32_16x16x32_bf16 v[70:73], v[236:239], v[228:231], v[70:73]
	v_mfma_f32_16x16x32_bf16 v[66:69], v[244:247], v[228:231], v[66:69]
	s_setprio 0
	s_mov_b32 m0, s44
	v_lshl_add_u64 v[248:249], s[36:37], 0, v[136:137]
	s_barrier
	ds_read_b128 v[178:181], v160 offset:16384
	ds_read_b128 v[182:185], v160 offset:17408
	ds_read_b128 v[186:189], v160 offset:18432
	ds_read_b128 v[190:193], v160 offset:19456
	ds_read_b128 v[204:207], v160 offset:20480
	ds_read_b128 v[208:211], v160 offset:21504
	ds_read_b128 v[212:215], v160 offset:22528
	ds_read_b128 v[228:231], v160 offset:23552
	global_load_lds_dwordx4 v[248:249], off
	v_lshl_add_u64 v[224:225], s[36:37], 0, v[132:133]
	s_mov_b32 m0, s45
	s_nop 0
	global_load_lds_dwordx4 v[224:225], off
	s_barrier
	s_waitcnt lgkmcnt(0)
	s_setprio 1
	s_waitcnt lgkmcnt(0)
	v_mfma_f32_16x16x32_bf16 v[62:65], v[162:165], v[178:181], v[62:65]
	v_mfma_f32_16x16x32_bf16 v[58:61], v[170:173], v[178:181], v[58:61]
	v_mfma_f32_16x16x32_bf16 v[54:57], v[162:165], v[186:189], v[54:57]
	v_mfma_f32_16x16x32_bf16 v[46:49], v[170:173], v[186:189], v[46:49]
	v_mfma_f32_16x16x32_bf16 v[38:41], v[162:165], v[204:207], v[38:41]
	v_mfma_f32_16x16x32_bf16 v[30:33], v[170:173], v[204:207], v[30:33]
	v_mfma_f32_16x16x32_bf16 v[22:25], v[162:165], v[212:215], v[22:25]
	v_mfma_f32_16x16x32_bf16 v[14:17], v[170:173], v[212:215], v[14:17]
	v_mfma_f32_16x16x32_bf16 v[62:65], v[166:169], v[182:185], v[62:65]
	v_mfma_f32_16x16x32_bf16 v[58:61], v[174:177], v[182:185], v[58:61]
	v_mfma_f32_16x16x32_bf16 v[54:57], v[166:169], v[190:193], v[54:57]
	v_mfma_f32_16x16x32_bf16 v[46:49], v[174:177], v[190:193], v[46:49]
	v_mfma_f32_16x16x32_bf16 v[38:41], v[166:169], v[208:211], v[38:41]
	v_mfma_f32_16x16x32_bf16 v[30:33], v[174:177], v[208:211], v[30:33]
	v_mfma_f32_16x16x32_bf16 v[22:25], v[166:169], v[228:231], v[22:25]
	v_mfma_f32_16x16x32_bf16 v[14:17], v[174:177], v[228:231], v[14:17]
	s_setprio 0
	s_barrier
	s_add_u32 s62, s4, 0x40000
	s_addc_u32 s63, s5, 0
	s_add_i32 s64, s64, s3
	v_lshl_add_u64 v[162:163], s[62:63], 0, v[134:135]
	s_mov_b32 m0, s64
	s_nop 0
	global_load_lds_dwordx4 v[162:163], off
	v_lshl_add_u64 v[162:163], s[62:63], 0, v[130:131]
	s_add_i32 m0, s64, 0x2000
	s_nop 0
	global_load_lds_dwordx4 v[162:163], off
	s_waitcnt vmcnt(6)
	s_barrier
	s_setprio 1
	v_mfma_f32_16x16x32_bf16 v[50:53], v[232:235], v[178:181], v[50:53]
	v_mfma_f32_16x16x32_bf16 v[42:45], v[240:243], v[178:181], v[42:45]
	v_mfma_f32_16x16x32_bf16 v[34:37], v[232:235], v[186:189], v[34:37]
	v_mfma_f32_16x16x32_bf16 v[26:29], v[240:243], v[186:189], v[26:29]
	v_mfma_f32_16x16x32_bf16 v[18:21], v[232:235], v[204:207], v[18:21]
	v_mfma_f32_16x16x32_bf16 v[10:13], v[240:243], v[204:207], v[10:13]
	v_mfma_f32_16x16x32_bf16 v[4:7], v[232:235], v[212:215], v[4:7]
	v_mfma_f32_16x16x32_bf16 v[0:3], v[240:243], v[212:215], v[0:3]
	v_mfma_f32_16x16x32_bf16 v[50:53], v[236:239], v[182:185], v[50:53]
	v_mfma_f32_16x16x32_bf16 v[42:45], v[244:247], v[182:185], v[42:45]
	v_mfma_f32_16x16x32_bf16 v[34:37], v[236:239], v[190:193], v[34:37]
	v_mfma_f32_16x16x32_bf16 v[26:29], v[244:247], v[190:193], v[26:29]
	v_mfma_f32_16x16x32_bf16 v[18:21], v[236:239], v[208:211], v[18:21]
	v_mfma_f32_16x16x32_bf16 v[10:13], v[244:247], v[208:211], v[10:13]
	v_mfma_f32_16x16x32_bf16 v[4:7], v[236:239], v[228:231], v[4:7]
	v_mfma_f32_16x16x32_bf16 v[0:3], v[244:247], v[228:231], v[0:3]
	s_setprio 0
	s_add_i32 s62, 0, 0x18000
	v_add_u32_e32 v8, s62, v146
	s_barrier
	ds_read_b128 v[162:165], v8
	ds_read_b128 v[166:169], v8 offset:1024
	ds_read_b128 v[170:173], v8 offset:2048
	ds_read_b128 v[174:177], v8 offset:3072
	s_add_u32 s36, s36, 0x40000
	s_addc_u32 s37, s37, 0
	s_mov_b32 m0, s46
	v_lshl_add_u64 v[232:233], s[36:37], 0, v[136:137]
	ds_read_b128 v[178:181], v160 offset:32768
	ds_read_b128 v[182:185], v160 offset:33792
	ds_read_b128 v[186:189], v160 offset:34816
	ds_read_b128 v[190:193], v160 offset:35840
	ds_read_b128 v[204:207], v160 offset:36864
	ds_read_b128 v[208:211], v160 offset:37888
	ds_read_b128 v[212:215], v160 offset:38912
	ds_read_b128 v[228:231], v160 offset:39936
	global_load_lds_dwordx4 v[232:233], off
	v_lshl_add_u64 v[232:233], s[36:37], 0, v[132:133]
	s_mov_b32 m0, s47
	s_nop 0
	global_load_lds_dwordx4 v[232:233], off
	s_waitcnt lgkmcnt(8)
	s_barrier
	s_waitcnt lgkmcnt(0)
	s_setprio 1
	s_waitcnt lgkmcnt(0)
	v_mfma_f32_16x16x32_bf16 v[126:129], v[162:165], v[178:181], v[126:129]
	v_mfma_f32_16x16x32_bf16 v[122:125], v[170:173], v[178:181], v[122:125]
	v_mfma_f32_16x16x32_bf16 v[118:121], v[162:165], v[186:189], v[118:121]
	v_mfma_f32_16x16x32_bf16 v[110:113], v[170:173], v[186:189], v[110:113]
	v_mfma_f32_16x16x32_bf16 v[102:105], v[162:165], v[204:207], v[102:105]
	v_mfma_f32_16x16x32_bf16 v[94:97], v[170:173], v[204:207], v[94:97]
	v_mfma_f32_16x16x32_bf16 v[86:89], v[162:165], v[212:215], v[86:89]
	v_mfma_f32_16x16x32_bf16 v[78:81], v[170:173], v[212:215], v[78:81]
	v_mfma_f32_16x16x32_bf16 v[126:129], v[166:169], v[182:185], v[126:129]
	v_mfma_f32_16x16x32_bf16 v[122:125], v[174:177], v[182:185], v[122:125]
	v_mfma_f32_16x16x32_bf16 v[118:121], v[166:169], v[190:193], v[118:121]
	v_mfma_f32_16x16x32_bf16 v[110:113], v[174:177], v[190:193], v[110:113]
	v_mfma_f32_16x16x32_bf16 v[102:105], v[166:169], v[208:211], v[102:105]
	v_mfma_f32_16x16x32_bf16 v[94:97], v[174:177], v[208:211], v[94:97]
	v_mfma_f32_16x16x32_bf16 v[86:89], v[166:169], v[228:231], v[86:89]
	v_mfma_f32_16x16x32_bf16 v[78:81], v[174:177], v[228:231], v[78:81]
	s_setprio 0
	s_barrier
	s_add_i32 s36, 0, 0x1c000
	s_add_i32 s37, s62, s3
	v_add_u32_e32 v8, s36, v146
	v_lshl_add_u64 v[144:145], v[144:145], 0, s[20:21]
	s_mov_b32 m0, s37
	ds_read_b128 v[232:235], v8
	ds_read_b128 v[236:239], v8 offset:1024
	ds_read_b128 v[240:243], v8 offset:2048
	ds_read_b128 v[244:247], v8 offset:3072
	global_load_lds_dwordx4 v[144:145], off
	v_lshl_add_u64 v[144:145], v[216:217], 0, s[20:21]
	s_add_i32 m0, s37, 0x2000
	s_nop 0
	global_load_lds_dwordx4 v[144:145], off
	s_barrier
	s_waitcnt lgkmcnt(0)
	s_setprio 1
	s_waitcnt lgkmcnt(0)
	v_mfma_f32_16x16x32_bf16 v[114:117], v[232:235], v[178:181], v[114:117]
	v_mfma_f32_16x16x32_bf16 v[106:109], v[240:243], v[178:181], v[106:109]
	v_mfma_f32_16x16x32_bf16 v[98:101], v[232:235], v[186:189], v[98:101]
	v_mfma_f32_16x16x32_bf16 v[90:93], v[240:243], v[186:189], v[90:93]
	v_mfma_f32_16x16x32_bf16 v[82:85], v[232:235], v[204:207], v[82:85]
	v_mfma_f32_16x16x32_bf16 v[74:77], v[240:243], v[204:207], v[74:77]
	v_mfma_f32_16x16x32_bf16 v[70:73], v[232:235], v[212:215], v[70:73]
	v_mfma_f32_16x16x32_bf16 v[66:69], v[240:243], v[212:215], v[66:69]
	v_mfma_f32_16x16x32_bf16 v[114:117], v[236:239], v[182:185], v[114:117]
	v_mfma_f32_16x16x32_bf16 v[106:109], v[244:247], v[182:185], v[106:109]
	v_mfma_f32_16x16x32_bf16 v[98:101], v[236:239], v[190:193], v[98:101]
	v_mfma_f32_16x16x32_bf16 v[90:93], v[244:247], v[190:193], v[90:93]
	v_mfma_f32_16x16x32_bf16 v[82:85], v[236:239], v[208:211], v[82:85]
	v_mfma_f32_16x16x32_bf16 v[74:77], v[244:247], v[208:211], v[74:77]
	v_mfma_f32_16x16x32_bf16 v[70:73], v[236:239], v[228:231], v[70:73]
	v_mfma_f32_16x16x32_bf16 v[66:69], v[244:247], v[228:231], v[66:69]
	s_setprio 0
	s_mov_b32 m0, s50
	v_lshl_add_u64 v[144:145], v[248:249], 0, s[20:21]
	s_barrier
	ds_read_b128 v[178:181], v160 offset:49152
	ds_read_b128 v[182:185], v160 offset:50176
	ds_read_b128 v[186:189], v160 offset:51200
	ds_read_b128 v[190:193], v160 offset:52224
	ds_read_b128 v[204:207], v160 offset:53248
	ds_read_b128 v[208:211], v160 offset:54272
	ds_read_b128 v[212:215], v160 offset:55296
	ds_read_b128 v[228:231], v160 offset:56320
	global_load_lds_dwordx4 v[144:145], off
	v_lshl_add_u64 v[144:145], v[224:225], 0, s[20:21]
	s_mov_b32 m0, s51
	s_nop 0
	global_load_lds_dwordx4 v[144:145], off
	s_barrier
	s_waitcnt lgkmcnt(0)
	s_setprio 1
	s_waitcnt lgkmcnt(0)
	v_mfma_f32_16x16x32_bf16 v[62:65], v[162:165], v[178:181], v[62:65]
	v_mfma_f32_16x16x32_bf16 v[58:61], v[170:173], v[178:181], v[58:61]
	v_mfma_f32_16x16x32_bf16 v[54:57], v[162:165], v[186:189], v[54:57]
	v_mfma_f32_16x16x32_bf16 v[46:49], v[170:173], v[186:189], v[46:49]
	v_mfma_f32_16x16x32_bf16 v[38:41], v[162:165], v[204:207], v[38:41]
	v_mfma_f32_16x16x32_bf16 v[30:33], v[170:173], v[204:207], v[30:33]
	v_mfma_f32_16x16x32_bf16 v[22:25], v[162:165], v[212:215], v[22:25]
	v_mfma_f32_16x16x32_bf16 v[14:17], v[170:173], v[212:215], v[14:17]
	v_mfma_f32_16x16x32_bf16 v[62:65], v[166:169], v[182:185], v[62:65]
	v_mfma_f32_16x16x32_bf16 v[58:61], v[174:177], v[182:185], v[58:61]
	v_mfma_f32_16x16x32_bf16 v[54:57], v[166:169], v[190:193], v[54:57]
	v_mfma_f32_16x16x32_bf16 v[46:49], v[174:177], v[190:193], v[46:49]
	v_mfma_f32_16x16x32_bf16 v[38:41], v[166:169], v[208:211], v[38:41]
	v_mfma_f32_16x16x32_bf16 v[30:33], v[174:177], v[208:211], v[30:33]
	v_mfma_f32_16x16x32_bf16 v[22:25], v[166:169], v[228:231], v[22:25]
	v_mfma_f32_16x16x32_bf16 v[14:17], v[174:177], v[228:231], v[14:17]
	s_setprio 0
	s_barrier
	s_add_u32 s4, s4, 0x40080
	s_addc_u32 s5, s5, 0
	s_add_i32 s36, s36, s3
	v_lshl_add_u64 v[144:145], s[4:5], 0, v[134:135]
	s_mov_b32 m0, s36
	s_nop 0
	global_load_lds_dwordx4 v[144:145], off
	v_lshl_add_u64 v[144:145], s[4:5], 0, v[130:131]
	s_add_i32 m0, s36, 0x2000
	s_nop 0
	global_load_lds_dwordx4 v[144:145], off
	s_waitcnt vmcnt(6)
	s_barrier
	s_setprio 1
	v_mfma_f32_16x16x32_bf16 v[50:53], v[232:235], v[178:181], v[50:53]
	v_mfma_f32_16x16x32_bf16 v[42:45], v[240:243], v[178:181], v[42:45]
	v_mfma_f32_16x16x32_bf16 v[34:37], v[232:235], v[186:189], v[34:37]
	v_mfma_f32_16x16x32_bf16 v[26:29], v[240:243], v[186:189], v[26:29]
	v_mfma_f32_16x16x32_bf16 v[18:21], v[232:235], v[204:207], v[18:21]
	v_mfma_f32_16x16x32_bf16 v[10:13], v[240:243], v[204:207], v[10:13]
	v_mfma_f32_16x16x32_bf16 v[4:7], v[232:235], v[212:215], v[4:7]
	v_mfma_f32_16x16x32_bf16 v[0:3], v[240:243], v[212:215], v[0:3]
	v_mfma_f32_16x16x32_bf16 v[50:53], v[236:239], v[182:185], v[50:53]
	v_mfma_f32_16x16x32_bf16 v[42:45], v[244:247], v[182:185], v[42:45]
	v_mfma_f32_16x16x32_bf16 v[34:37], v[236:239], v[190:193], v[34:37]
	v_mfma_f32_16x16x32_bf16 v[26:29], v[244:247], v[190:193], v[26:29]
	v_mfma_f32_16x16x32_bf16 v[18:21], v[236:239], v[208:211], v[18:21]
	v_mfma_f32_16x16x32_bf16 v[10:13], v[244:247], v[208:211], v[10:13]
	v_mfma_f32_16x16x32_bf16 v[4:7], v[236:239], v[228:231], v[4:7]
	v_mfma_f32_16x16x32_bf16 v[0:3], v[244:247], v[228:231], v[0:3]
	s_setprio 0
	s_add_i32 s43, s43, 2
	s_add_u32 s0, s0, 0x100
	s_addc_u32 s1, s1, 0
	s_add_u32 s41, s41, 0x100
	s_addc_u32 s42, s42, 0
	s_cmp_gt_u32 s43, 13
	s_barrier
	s_cbranch_scc0 .LBB0_521
	s_and_b32 s4, s26, -2
	s_cmp_eq_u32 s4, 6
	s_cselect_b64 s[0:1], -1, 0
	s_cmp_lg_u32 s4, 6
	s_cselect_b64 s[42:43], -1, 0
	s_lshl_b32 s19, s28, 3
	s_ashr_i32 s4, s28, 4
	s_add_i32 s5, s28, 0xffffff80
	s_and_b32 s19, s19, 0x78
	s_cmpk_lt_i32 s28, 0x80
	s_cselect_b32 s4, s4, s5
	s_cselect_b32 s5, 0, 0x2000000
	s_cselect_b32 s62, s19, 0
	s_cselect_b32 s19, 18, 14
	s_add_u32 s25, s75, s5
	s_addc_u32 s29, s76, 0
	s_lshl_b32 s4, s4, 3
	s_ashr_i32 s5, s4, 31
	s_lshl_b64 s[4:5], s[4:5], s19
	s_lshl_b64 s[4:5], s[4:5], 1
	s_add_u32 s36, s25, s4
	s_addc_u32 s37, s29, s5
	s_lshl_b32 s4, s26, 8
	s_lshl_b32 s63, s28, 8
	s_add_i32 s5, s4, 0xfffffe00
	s_cmp_lt_i32 s26, 6
	s_cselect_b32 s40, s4, s5
	s_lshl_b32 s25, s26, 2
	s_add_i32 s4, s62, s54
	s_add_i32 s25, s25, s53
	s_lshl_b32 s28, s4, 11
	v_add_u32_e32 v8, s63, v139
	v_mov_b64_e32 v[144:145], s[70:71]
	s_ashr_i32 s41, s40, 31
	v_or_b32_e32 v161, s28, v147
	v_mad_i64_i32 v[144:145], s[4:5], v8, s77, v[144:145]
	s_lshl_b32 s64, s25, s19
	v_lshl_add_u64 v[144:145], s[40:41], 1, v[144:145]
	s_lshl_b32 s26, s52, 1
	v_cvt_pk_bf16_f32 v126, v126, v127
	v_cvt_pk_bf16_f32 v127, v128, v129
	v_cvt_pk_bf16_f32 v128, v122, v123
	v_add_u32_e32 v122, s64, v161
	v_lshl_add_u64 v[144:145], v[144:145], 0, s[26:27]
	v_lshlrev_b32_e32 v8, 1, v138
	v_or_b32_e32 v122, v122, v159
	v_mov_b32_e32 v123, v9
	v_lshl_add_u64 v[144:145], v[144:145], 0, v[8:9]
	v_lshl_add_u64 v[122:123], v[122:123], 1, s[36:37]
	v_cvt_pk_bf16_f32 v129, v124, v125
	v_cndmask_b32_e64 v123, v145, v123, s[0:1]
	v_cndmask_b32_e64 v122, v144, v122, s[0:1]
	s_mov_b64 s[4:5], -1
	s_and_b64 vcc, exec, s[0:1]
	global_store_dwordx4 v[122:123], v[126:129], off nt
	s_cbranch_vccnz .LBB0_524
	s_mov_b64 s[4:5], 0x100
	v_lshl_add_u64 v[122:123], v[144:145], 0, s[4:5]
	s_mov_b64 s[4:5], 0

.LBB0_526:
	v_cvt_pk_bf16_f32 v114, v114, v115
	v_cvt_pk_bf16_f32 v115, v116, v117
	v_cvt_pk_bf16_f32 v116, v106, v107
	v_cvt_pk_bf16_f32 v117, v108, v109
	v_add_u32_e32 v108, s63, v148
	v_mov_b64_e32 v[106:107], s[70:71]
	global_store_dwordx4 v[122:123], v[114:117], off nt
	v_mad_i64_i32 v[106:107], s[4:5], v108, s77, v[106:107]
	s_nop 0
	v_or_b32_e32 v114, s28, v149
	v_lshl_add_u64 v[106:107], s[40:41], 1, v[106:107]
	v_cvt_pk_bf16_f32 v110, v110, v111
	v_cvt_pk_bf16_f32 v111, v112, v113
	v_add_u32_e32 v112, s64, v114
	v_lshl_add_u64 v[106:107], v[106:107], 0, s[26:27]
	v_or_b32_e32 v112, v112, v159
	v_mov_b32_e32 v113, v9
	v_lshl_add_u64 v[106:107], v[106:107], 0, v[8:9]
	v_lshl_add_u64 v[112:113], v[112:113], 1, s[36:37]
	v_cvt_pk_bf16_f32 v108, v118, v119
	v_cvt_pk_bf16_f32 v109, v120, v121
	v_cndmask_b32_e64 v113, v107, v113, s[0:1]
	v_cndmask_b32_e64 v112, v106, v112, s[0:1]
	global_store_dwordx4 v[112:113], v[108:111], off nt
	s_andn2_b64 vcc, exec, s[42:43]
	s_mov_b64 s[28:29], -1
	v_cndmask_b32_e64 v108, 0, 1, s[42:43]
	v_cmp_ne_u32_e64 s[4:5], 1, v108
	s_cbranch_vccnz .LBB0_528
	s_mov_b64 s[28:29], 0x100
	v_lshl_add_u64 v[108:109], v[106:107], 0, s[28:29]
	s_mov_b64 s[28:29], 0

.LBB0_530:
	v_cvt_pk_bf16_f32 v98, v98, v99
	v_cvt_pk_bf16_f32 v99, v100, v101
	v_cvt_pk_bf16_f32 v100, v90, v91
	v_cvt_pk_bf16_f32 v101, v92, v93
	s_add_i32 s28, s62, s55
	v_add_u32_e32 v92, s63, v150
	v_mov_b64_e32 v[90:91], s[70:71]
	global_store_dwordx4 v[108:109], v[98:101], off nt
	s_and_b64 vcc, exec, s[4:5]
	s_nop 0
	v_lshl_or_b32 v98, s28, 11, v147
	v_mad_i64_i32 v[90:91], s[28:29], v92, s77, v[90:91]
	v_lshl_add_u64 v[90:91], s[40:41], 1, v[90:91]
	v_lshl_add_u64 v[90:91], v[90:91], 0, s[26:27]
	v_lshl_add_u64 v[92:93], v[90:91], 0, v[8:9]
	v_add_u32_e32 v90, s64, v98
	v_or_b32_e32 v90, v90, v159
	v_mov_b32_e32 v91, v9
	v_lshl_add_u64 v[90:91], v[90:91], 1, s[36:37]
	v_cvt_pk_bf16_f32 v100, v102, v103
	v_cvt_pk_bf16_f32 v101, v104, v105
	v_cvt_pk_bf16_f32 v102, v94, v95
	v_cvt_pk_bf16_f32 v103, v96, v97
	v_cndmask_b32_e64 v91, v93, v91, s[0:1]
	v_cndmask_b32_e64 v90, v92, v90, s[0:1]
	s_mov_b64 s[28:29], -1
	global_store_dwordx4 v[90:91], v[100:103], off nt
	s_cbranch_vccnz .LBB0_532
	s_mov_b64 s[28:29], 0x100
	v_lshl_add_u64 v[90:91], v[92:93], 0, s[28:29]
	s_mov_b64 s[28:29], 0

.LBB0_534:
	v_cvt_pk_bf16_f32 v82, v82, v83
	v_cvt_pk_bf16_f32 v83, v84, v85
	v_cvt_pk_bf16_f32 v84, v74, v75
	v_cvt_pk_bf16_f32 v85, v76, v77
	s_add_i32 s28, s62, s56
	v_add_u32_e32 v76, s63, v151
	v_mov_b64_e32 v[74:75], s[70:71]
	global_store_dwordx4 v[90:91], v[82:85], off nt
	s_and_b64 vcc, exec, s[4:5]
	s_nop 0
	v_lshl_or_b32 v82, s28, 11, v152
	v_mad_i64_i32 v[74:75], s[28:29], v76, s77, v[74:75]
	v_lshl_add_u64 v[74:75], s[40:41], 1, v[74:75]
	v_lshl_add_u64 v[74:75], v[74:75], 0, s[26:27]
	v_lshl_add_u64 v[76:77], v[74:75], 0, v[8:9]
	v_add_u32_e32 v74, s64, v82
	v_or_b32_e32 v74, v74, v159
	v_mov_b32_e32 v75, v9
	v_lshl_add_u64 v[74:75], v[74:75], 1, s[36:37]
	v_cvt_pk_bf16_f32 v84, v86, v87
	v_cvt_pk_bf16_f32 v85, v88, v89
	v_cvt_pk_bf16_f32 v86, v78, v79
	v_cvt_pk_bf16_f32 v87, v80, v81
	v_cndmask_b32_e64 v75, v77, v75, s[0:1]
	v_cndmask_b32_e64 v74, v76, v74, s[0:1]
	s_mov_b64 s[28:29], -1
	global_store_dwordx4 v[74:75], v[84:87], off nt
	s_cbranch_vccnz .LBB0_536
	s_mov_b64 s[28:29], 0x100
	v_lshl_add_u64 v[74:75], v[76:77], 0, s[28:29]
	s_mov_b64 s[28:29], 0

.LBB0_538:
	v_cvt_pk_bf16_f32 v70, v70, v71
	v_cvt_pk_bf16_f32 v71, v72, v73
	v_cvt_pk_bf16_f32 v72, v66, v67
	v_cvt_pk_bf16_f32 v73, v68, v69
	s_add_i32 s28, s62, s57
	v_add_u32_e32 v69, s63, v153
	v_mov_b64_e32 v[66:67], s[70:71]
	v_lshl_or_b32 v68, s28, 11, v147
	v_mad_i64_i32 v[66:67], s[28:29], v69, s77, v[66:67]
	v_lshl_add_u64 v[66:67], s[40:41], 1, v[66:67]
	v_cvt_pk_bf16_f32 v62, v62, v63
	v_cvt_pk_bf16_f32 v63, v64, v65
	v_cvt_pk_bf16_f32 v64, v58, v59
	v_add_u32_e32 v58, s64, v68
	v_lshl_add_u64 v[66:67], v[66:67], 0, s[26:27]
	v_or_b32_e32 v58, v58, v159
	v_mov_b32_e32 v59, v9
	v_lshl_add_u64 v[66:67], v[66:67], 0, v[8:9]
	v_lshl_add_u64 v[58:59], v[58:59], 1, s[36:37]
	v_cvt_pk_bf16_f32 v65, v60, v61
	v_cndmask_b32_e64 v59, v67, v59, s[0:1]
	v_cndmask_b32_e64 v58, v66, v58, s[0:1]
	s_and_b64 vcc, exec, s[4:5]
	s_mov_b64 s[28:29], -1
	global_store_dwordx4 v[74:75], v[70:73], off nt
	global_store_dwordx4 v[58:59], v[62:65], off nt
	s_cbranch_vccnz .LBB0_540
	s_mov_b64 s[28:29], 0x100
	v_lshl_add_u64 v[58:59], v[66:67], 0, s[28:29]
	s_mov_b64 s[28:29], 0

.LBB0_542:
	v_cvt_pk_bf16_f32 v50, v50, v51
	v_cvt_pk_bf16_f32 v51, v52, v53
	v_cvt_pk_bf16_f32 v52, v42, v43
	v_cvt_pk_bf16_f32 v53, v44, v45
	s_add_i32 s28, s62, s58
	v_add_u32_e32 v44, s63, v154
	v_mov_b64_e32 v[42:43], s[70:71]
	global_store_dwordx4 v[58:59], v[50:53], off nt
	s_and_b64 vcc, exec, s[4:5]
	s_nop 0
	v_lshl_or_b32 v50, s28, 11, v155
	v_mad_i64_i32 v[42:43], s[28:29], v44, s77, v[42:43]
	v_lshl_add_u64 v[42:43], s[40:41], 1, v[42:43]
	v_lshl_add_u64 v[42:43], v[42:43], 0, s[26:27]
	v_lshl_add_u64 v[44:45], v[42:43], 0, v[8:9]
	v_add_u32_e32 v42, s64, v50
	v_or_b32_e32 v42, v42, v159
	v_mov_b32_e32 v43, v9
	v_lshl_add_u64 v[42:43], v[42:43], 1, s[36:37]
	v_cvt_pk_bf16_f32 v52, v54, v55
	v_cvt_pk_bf16_f32 v53, v56, v57
	v_cvt_pk_bf16_f32 v54, v46, v47
	v_cvt_pk_bf16_f32 v55, v48, v49
	v_cndmask_b32_e64 v43, v45, v43, s[0:1]
	v_cndmask_b32_e64 v42, v44, v42, s[0:1]
	s_mov_b64 s[28:29], -1
	global_store_dwordx4 v[42:43], v[52:55], off nt
	s_cbranch_vccnz .LBB0_544
	s_mov_b64 s[28:29], 0x100
	v_lshl_add_u64 v[42:43], v[44:45], 0, s[28:29]
	s_mov_b64 s[28:29], 0

.LBB0_546:
	v_cvt_pk_bf16_f32 v34, v34, v35
	v_cvt_pk_bf16_f32 v35, v36, v37
	v_cvt_pk_bf16_f32 v36, v26, v27
	v_cvt_pk_bf16_f32 v37, v28, v29
	s_add_i32 s28, s62, s59
	v_add_u32_e32 v28, s63, v156
	v_mov_b64_e32 v[26:27], s[70:71]
	global_store_dwordx4 v[42:43], v[34:37], off nt
	s_and_b64 vcc, exec, s[4:5]
	s_nop 0
	v_lshl_or_b32 v34, s28, 11, v147
	v_mad_i64_i32 v[26:27], s[28:29], v28, s77, v[26:27]
	v_lshl_add_u64 v[26:27], s[40:41], 1, v[26:27]
	v_lshl_add_u64 v[26:27], v[26:27], 0, s[26:27]
	v_lshl_add_u64 v[28:29], v[26:27], 0, v[8:9]
	v_add_u32_e32 v26, s64, v34
	v_or_b32_e32 v26, v26, v159
	v_mov_b32_e32 v27, v9
	v_lshl_add_u64 v[26:27], v[26:27], 1, s[36:37]
	v_cvt_pk_bf16_f32 v36, v38, v39
	v_cvt_pk_bf16_f32 v37, v40, v41
	v_cvt_pk_bf16_f32 v38, v30, v31
	v_cvt_pk_bf16_f32 v39, v32, v33
	v_cndmask_b32_e64 v27, v29, v27, s[0:1]
	v_cndmask_b32_e64 v26, v28, v26, s[0:1]
	s_mov_b64 s[28:29], -1
	global_store_dwordx4 v[26:27], v[36:39], off nt
	s_cbranch_vccnz .LBB0_548
	s_mov_b64 s[28:29], 0x100
	v_lshl_add_u64 v[26:27], v[28:29], 0, s[28:29]
	s_mov_b64 s[28:29], 0

.LBB0_550:
	v_cvt_pk_bf16_f32 v18, v18, v19
	v_cvt_pk_bf16_f32 v19, v20, v21
	v_cvt_pk_bf16_f32 v20, v10, v11
	v_cvt_pk_bf16_f32 v21, v12, v13
	v_add_u32_e32 v12, s63, v157
	v_mov_b64_e32 v[10:11], s[70:71]
	v_mad_i64_i32 v[10:11], s[28:29], v12, s77, v[10:11]
	s_add_i32 s62, s62, s60
	v_lshl_add_u64 v[10:11], s[40:41], 1, v[10:11]
	global_store_dwordx4 v[26:27], v[18:21], off nt
	v_lshl_add_u64 v[10:11], v[10:11], 0, s[26:27]
	v_lshl_add_u64 v[12:13], v[10:11], 0, v[8:9]
	v_lshl_or_b32 v18, s62, 11, v158
	v_add_u32_e32 v8, s64, v18
	v_or_b32_e32 v8, v8, v159
	v_lshl_add_u64 v[10:11], v[8:9], 1, s[36:37]
	v_cvt_pk_bf16_f32 v20, v22, v23
	v_cvt_pk_bf16_f32 v21, v24, v25
	v_cvt_pk_bf16_f32 v22, v14, v15
	v_cvt_pk_bf16_f32 v23, v16, v17
	v_cndmask_b32_e64 v11, v13, v11, s[0:1]
	v_cndmask_b32_e64 v10, v12, v10, s[0:1]
	s_and_b64 vcc, exec, s[4:5]
	s_mov_b64 s[0:1], -1
	global_store_dwordx4 v[10:11], v[20:23], off nt
	s_cbranch_vccnz .LBB0_552
	s_mov_b64 s[0:1], 0x100
	v_lshl_add_u64 v[10:11], v[12:13], 0, s[0:1]
	s_mov_b64 s[0:1], 0
